# P4+P6 stage_T loads batched (all tile loads in flight, one wait), seams as before
# speedup vs baseline: 1.0106x; 1.0071x over previous
; #define LAS __attribute__((address_space(3)))
; template <int NROWS, int NCOLS, int VS>
; __device__ __forceinline__ void stage_T(LAS bf16_t* dstT, const bf16_t* src, long r0, int ld, int col0, long rmin, int tid) {
;     constexpr int NCH = NCOLS / 8, TOT = NROWS * NCH;
; #pragma unroll
;     for (int i = 0; i < TOT / 512; ++i) {
;         const int idx = tid + 512 * i;
;         int ch, j;
;         if (NCH == 16) { ch = (idx & 7) + 8 * ((idx >> 6) & 1); j = ((idx >> 3) & 7) + 8 * (idx >> 7); } else { ch = idx & 7; j = idx >> 3; }
;         const long r = r0 + j;
;         u32x4 v = {0u, 0u, 0u, 0u};
;         if (r >= rmin) v = STG_NT ? __builtin_nontemporal_load((const u32x4*)(src + r * ld + col0 + 8 * ch)) : *(const u32x4*)(src + r * ld + col0 + 8 * ch);
;         LAS bf16_t* d = dstT + (8 * ch) * VS + (j ^ ((ch & 15) << 3));
;         d[0 * VS] = (bf16_t)(v.x & 0xffffu); d[1 * VS] = (bf16_t)(v.x >> 16); d[2 * VS] = (bf16_t)(v.y & 0xffffu); d[3 * VS] = (bf16_t)(v.y >> 16);
;         d[4 * VS] = (bf16_t)(v.z & 0xffffu); d[5 * VS] = (bf16_t)(v.z >> 16); d[6 * VS] = (bf16_t)(v.w & 0xffffu); d[7 * VS] = (bf16_t)(v.w >> 16);
;     }
; }
; __device__ __forceinline__ void swa_item(int it, LAS unsigned char* lds, const bf16_t* SQ, const bf16_t* SK, const bf16_t* SV, const float* sinks, bf16_t* MIX, int tid, int wid, int lane) {
;     ...
;     __syncthreads();
;     stage_T<256, 64, VS>(VT, SV, rb + pos0 - 128, 128, kvh * 64, rb, tid);
;     __syncthreads();
.LBB0_1023:
	s_ashr_i32 s0, s56, 7
	s_bfe_u32 s57, s56, 0x50002
	s_ashr_i32 s1, s0, 31
	s_lshl_b64 s[40:41], s[0:1], 12
	s_lshl_b32 s64, s57, 7
	s_bfe_u32 s10, s56, 0x10001
	s_or_b32 s0, s40, s64
	s_add_u32 s0, s0, 0xffffff80
	s_addc_u32 s1, s41, -1
	s_lshl_b32 s14, s10, 7
	v_mov_b32_e32 v7, s1
	v_or_b32_e32 v6, s0, v90
	v_lshl_add_u64 v[8:9], v[92:93], 0, s[14:15]
	v_cmp_le_i64_e32 vcc, s[40:41], v[6:7]
	v_mov_b32_e32 v236, 0
	v_mov_b32_e32 v237, 0
	v_mov_b32_e32 v238, 0
	v_mov_b32_e32 v239, 0
	v_mov_b32_e32 v240, 0
	v_mov_b32_e32 v241, 0
	v_mov_b32_e32 v242, 0
	v_mov_b32_e32 v243, 0
	v_mov_b32_e32 v244, 0
	v_mov_b32_e32 v245, 0
	v_mov_b32_e32 v246, 0
	v_mov_b32_e32 v247, 0
	v_mov_b32_e32 v248, 0
	v_mov_b32_e32 v249, 0
	v_mov_b32_e32 v250, 0
	v_mov_b32_e32 v251, 0
	s_waitcnt vmcnt(0)
	s_barrier
	s_and_saveexec_b64 s[6:7], vcc
	s_cbranch_execz .LBB0_1025
	v_lshlrev_b64 v[2:3], 8, v[6:7]
	v_lshl_add_u64 v[2:3], v[8:9], 0, v[2:3]
	global_load_dwordx4 v[236:239], v[2:3], off
.LBB0_1025:
	s_or_b64 exec, exec, s[6:7]
	v_lshl_add_u64 v[10:11], s[0:1], 0, v[94:95]
	v_cmp_le_i64_e32 vcc, s[40:41], v[10:11]
	s_and_saveexec_b64 s[6:7], vcc
	s_cbranch_execz .LBB0_1027
	v_lshlrev_b64 v[4:5], 8, v[10:11]
	v_lshl_add_u64 v[4:5], v[8:9], 0, v[4:5]
	global_load_dwordx4 v[240:243], v[4:5], off
.LBB0_1027:
	s_or_b64 exec, exec, s[6:7]
	v_lshl_add_u64 v[6:7], s[0:1], 0, v[96:97]
	v_cmp_le_i64_e32 vcc, s[40:41], v[6:7]
	s_and_saveexec_b64 s[6:7], vcc
	s_cbranch_execz .LBB0_1029
	v_lshlrev_b64 v[2:3], 8, v[6:7]
	v_lshl_add_u64 v[2:3], v[8:9], 0, v[2:3]
	global_load_dwordx4 v[244:247], v[2:3], off
.LBB0_1029:
	s_or_b64 exec, exec, s[6:7]
	v_lshl_add_u64 v[6:7], s[0:1], 0, v[98:99]
	v_cmp_le_i64_e32 vcc, s[40:41], v[6:7]
	s_and_saveexec_b64 s[0:1], vcc
	s_cbranch_execz .LBB0_1031
	v_lshlrev_b64 v[2:3], 8, v[6:7]
	v_lshl_add_u64 v[2:3], v[8:9], 0, v[2:3]
	global_load_dwordx4 v[248:251], v[2:3], off
; #define LAS __attribute__((address_space(3)))
; template <int NROWS, int NCOLS, int VS>
; __device__ __forceinline__ void stage_T(LAS bf16_t* dstT, const bf16_t* src, long r0, int ld, int col0, long rmin, int tid) {
;     ...
;         LAS bf16_t* d = dstT + (8 * ch) * VS + (j ^ ((ch & 15) << 3));
;         d[0 * VS] = (bf16_t)(v.x & 0xffffu); d[1 * VS] = (bf16_t)(v.x >> 16); d[2 * VS] = (bf16_t)(v.y & 0xffffu); d[3 * VS] = (bf16_t)(v.y >> 16);
;         d[4 * VS] = (bf16_t)(v.z & 0xffffu); d[5 * VS] = (bf16_t)(v.z >> 16); d[6 * VS] = (bf16_t)(v.w & 0xffffu); d[7 * VS] = (bf16_t)(v.w >> 16);
;     }
; }
; __device__ __forceinline__ void swa_item(int it, LAS unsigned char* lds, const bf16_t* SQ, const bf16_t* SK, const bf16_t* SV, const float* sinks, bf16_t* MIX, int tid, int wid, int lane) {
;     ...
;     const int x = lane & 31, hi = lane >> 5;
; #pragma unroll 1
;     for (int tk = wid; tk < 16; tk += 8) {
;         const int hl = tk >> 2, qt = tk & 3, head = kvh * 8 + hh * 4 + hl;
;         const long qrow = rb + pos0 + 32 * qt + x;
;         bf16x8 qf[4];
; #pragma unroll
;         for (int ks = 0; ks < 4; ++ks) qf[ks] = *(const bf16x8*)(SQ + qrow * 1024 + head * 64 + 16 * ks + 8 * hi);
;         f32x16 st[5];
; #pragma unroll
;         for (int t = 0; t < 5; ++t) {
;             int kp = pos0 + 32 * qt - 128 + 32 * t + x; if (kp < 0) kp = 0;
;             const bf16_t* kptr = SK + (rb + kp) * 128 + kvh * 64 + 8 * hi;
.LBB0_1031:
	s_or_b64 exec, exec, s[0:1]
	v_readlane_b32 s0, v255, 0
	v_readlane_b32 s1, v255, 1
	s_andn2_b64 vcc, exec, s[0:1]
	s_waitcnt vmcnt(0)
	ds_write_b16 v127, v236
	ds_write_b16_d16_hi v127, v236 offset:528
	ds_write_b16 v127, v237 offset:1056
	ds_write_b16_d16_hi v127, v237 offset:1584
	ds_write_b16 v127, v238 offset:2112
	ds_write_b16_d16_hi v127, v238 offset:2640
	ds_write_b16 v127, v239 offset:3168
	ds_write_b16_d16_hi v127, v239 offset:3696
	ds_write_b16 v128, v240
	ds_write_b16_d16_hi v128, v240 offset:528
	ds_write_b16 v128, v241 offset:1056
	ds_write_b16_d16_hi v128, v241 offset:1584
	ds_write_b16 v128, v242 offset:2112
	ds_write_b16_d16_hi v128, v242 offset:2640
	ds_write_b16 v128, v243 offset:3168
	ds_write_b16_d16_hi v128, v243 offset:3696
	ds_write_b16 v130, v244
	ds_write_b16_d16_hi v130, v244 offset:528
	ds_write_b16 v130, v245 offset:1056
	ds_write_b16_d16_hi v130, v245 offset:1584
	ds_write_b16 v130, v246 offset:2112
	ds_write_b16_d16_hi v130, v246 offset:2640
	ds_write_b16 v130, v247 offset:3168
	ds_write_b16_d16_hi v130, v247 offset:3696
	ds_write_b16 v131, v248
	ds_write_b16_d16_hi v131, v248 offset:528
	ds_write_b16 v131, v249 offset:1056
	ds_write_b16_d16_hi v131, v249 offset:1584
	ds_write_b16 v131, v250 offset:2112
	ds_write_b16_d16_hi v131, v250 offset:2640
	ds_write_b16 v131, v251 offset:3168
	ds_write_b16_d16_hi v131, v251 offset:3696
	s_waitcnt lgkmcnt(0)
	s_barrier
	s_cbranch_vccnz .LBB0_1022
	s_lshr_b32 s0, s56, 1
	s_and_b32 s0, s0, 1
	s_lshl_b32 s0, s0, 3
	s_add_i32 s0, s33, s0
	s_and_b32 s7, s49, 4
	s_add_i32 s14, s0, s7
	v_readlane_b32 s68, v254, 18
	s_lshr_b32 s1, s56, 2
	s_lshl_b32 s6, s10, 6
	s_lshl_b32 s0, s14, 2
	v_readlane_b32 s70, v254, 20
	v_readlane_b32 s71, v254, 21
	s_add_u32 s10, s70, s0
	s_addc_u32 s11, s71, 0
	s_and_b32 s0, s1, 31
	v_and_b32_e32 v5, 64, v87
	s_lshl_b32 s60, s0, 7
	s_lshl_b64 s[44:45], s[14:15], 7
	s_lshl_b32 s14, s6, 1
	v_xor_b32_e32 v4, 32, v87
	v_add_u32_e32 v5, 64, v5
	s_cmp_eq_u32 s57, 0
	v_cmp_lt_i32_e32 vcc, v4, v5
	v_readlane_b32 s6, v255, 2
	s_cselect_b64 s[0:1], -1, 0
	v_cndmask_b32_e32 v4, v87, v4, vcc
	s_add_i32 s64, s64, s6
	v_lshlrev_b32_e32 v174, 2, v4
	v_or_b32_e32 v4, s64, v91
	v_cndmask_b32_e64 v4, v4, 0, s[0:1]
	v_ashrrev_i32_e32 v5, 31, v4
	v_lshl_add_u64 v[4:5], s[40:41], 0, v[4:5]
	v_lshl_add_u64 v[2:3], v[100:101], 0, s[14:15]
	v_lshlrev_b64 v[4:5], 8, v[4:5]
	s_cmpk_gt_i32 s64, 0xffdf
	v_lshl_add_u64 v[108:109], v[2:3], 0, v[4:5]
	v_add_u32_e32 v4, s64, v132
	s_cselect_b64 vcc, -1, 0
	v_cndmask_b32_e32 v4, 0, v4, vcc
	v_ashrrev_i32_e32 v5, 31, v4
	v_lshl_add_u64 v[4:5], s[40:41], 0, v[4:5]
	v_lshlrev_b64 v[4:5], 8, v[4:5]
	s_cmpk_gt_i32 s64, 0xffbf
	v_lshl_add_u64 v[110:111], v[2:3], 0, v[4:5]
	v_add_u32_e32 v4, s64, v122
	s_cselect_b64 vcc, -1, 0
	v_cndmask_b32_e32 v4, 0, v4, vcc
	v_ashrrev_i32_e32 v5, 31, v4
	v_lshl_add_u64 v[4:5], s[40:41], 0, v[4:5]
	v_readlane_b32 s6, v255, 3
	v_lshlrev_b64 v[4:5], 8, v[4:5]
	s_cmpk_gt_i32 s64, 0xff9f
	v_readlane_b32 s7, v255, 4
	v_lshl_add_u64 v[112:113], v[2:3], 0, v[4:5]
	v_add_u32_e32 v4, s64, v133
	s_cselect_b64 vcc, -1, 0
	v_add_u32_e32 v88, s64, v134
	s_or_b64 s[64:65], s[6:7], s[0:1]
	v_readlane_b32 s6, v255, 5
	v_readlane_b32 s69, v254, 19
	v_readlane_b32 s7, v255, 6
	s_or_b64 s[68:69], s[6:7], s[0:1]
	v_readlane_b32 s6, v255, 7
	v_readlane_b32 s7, v255, 8
	s_or_b64 s[70:71], s[6:7], s[0:1]
	v_readlane_b32 s6, v255, 9
	v_readlane_b32 s72, v254, 22
	v_readlane_b32 s73, v254, 23
	v_readlane_b32 s7, v255, 10
	s_or_b64 s[72:73], s[6:7], s[0:1]
	v_readlane_b32 s6, v255, 11
	v_readlane_b32 s74, v254, 24
	v_readlane_b32 s75, v254, 25
	v_readlane_b32 s7, v255, 12
	s_or_b64 s[74:75], s[6:7], s[0:1]
	v_readlane_b32 s6, v255, 13
	v_readlane_b32 s76, v254, 26
	v_readlane_b32 s77, v254, 27
	v_readlane_b32 s7, v255, 14
	s_or_b64 s[76:77], s[6:7], s[0:1]
	v_readlane_b32 s6, v255, 15
	v_readlane_b32 s78, v254, 28
	v_readlane_b32 s79, v254, 29
	v_readlane_b32 s7, v255, 16
	s_or_b64 s[78:79], s[6:7], s[0:1]
	v_readlane_b32 s6, v255, 17
	v_readlane_b32 s80, v254, 30
	v_readlane_b32 s81, v254, 31
	v_readlane_b32 s7, v255, 18
	s_or_b64 s[80:81], s[6:7], s[0:1]
	v_readlane_b32 s6, v255, 19
	v_readlane_b32 s82, v254, 32
	v_readlane_b32 s83, v254, 33
	v_readlane_b32 s7, v255, 20
	s_or_b64 s[82:83], s[6:7], s[0:1]
	v_readlane_b32 s6, v255, 21
	v_readlane_b32 s7, v255, 22
	s_mov_b64 s[22:23], s[84:85]
	s_or_b64 s[84:85], s[6:7], s[0:1]
	v_readlane_b32 s6, v255, 23
	v_readlane_b32 s7, v255, 24
	s_mov_b32 s26, s87
	s_mov_b32 s61, s86
	s_or_b64 s[86:87], s[6:7], s[0:1]
	v_readlane_b32 s6, v255, 25
	v_readlane_b32 s7, v255, 26
	s_or_b64 s[88:89], s[6:7], s[0:1]
	v_readlane_b32 s6, v255, 27
	v_readlane_b32 s7, v255, 28
	s_or_b64 s[90:91], s[6:7], s[0:1]
	v_readlane_b32 s6, v255, 29
	v_readlane_b32 s7, v255, 30
	s_or_b64 s[92:93], s[6:7], s[0:1]
	v_readlane_b32 s6, v255, 31
	v_readlane_b32 s7, v255, 32
	s_mov_b64 s[18:19], s[36:37]
	s_mov_b64 s[36:37], s[94:95]
	s_or_b64 s[94:95], s[6:7], s[0:1]
	v_readlane_b32 s6, v255, 33
	v_readlane_b32 s7, v255, 34
	s_mov_b64 s[52:53], s[96:97]
	v_cndmask_b32_e32 v4, 0, v4, vcc
	s_and_b64 s[96:97], s[6:7], s[0:1]
	v_readlane_b32 s6, v255, 35
	v_ashrrev_i32_e32 v5, 31, v4
	v_readlane_b32 s7, v255, 36
	v_lshl_add_u64 v[4:5], s[40:41], 0, v[4:5]
	s_or_b64 s[66:67], s[4:5], s[0:1]
	s_and_b64 s[0:1], s[0:1], s[6:7]
	s_or_b32 s6, s57, s48
	v_lshlrev_b64 v[4:5], 8, v[4:5]
	s_cmp_eq_u32 s6, 0
	v_lshl_add_u64 v[114:115], v[2:3], 0, v[4:5]
	v_lshl_add_u64 v[4:5], s[40:41], 0, v[88:89]
	s_cselect_b64 s[6:7], -1, 0
	s_add_u32 s40, s60, s40
	v_lshlrev_b64 v[4:5], 8, v[4:5]
	s_addc_u32 s41, 0, s41
	v_lshl_add_u64 v[116:117], v[2:3], 0, v[4:5]
	v_lshl_add_u64 v[2:3], s[40:41], 0, v[102:103]
	v_lshlrev_b64 v[4:5], 11, v[2:3]
	v_lshlrev_b64 v[2:3], 12, v[2:3]
	v_lshl_add_u64 v[4:5], v[4:5], 0, s[44:45]
	v_lshl_add_u64 v[2:3], v[2:3], 0, s[44:45]
	v_readlane_b32 s14, v255, 37
	v_lshl_add_u64 v[118:119], v[104:105], 0, v[4:5]
	v_lshl_add_u64 v[120:121], v[106:107], 0, v[2:3]
	v_mov_b32_e32 v88, s14

; #define LAS __attribute__((address_space(3)))
; __device__ __forceinline__ void kv_item2(int it0, LAS unsigned char* lds, const bf16_t* RK, const bf16_t* RV, float* STATE, int tid, int wid, int lane) {
;     constexpr int VS = 136, TILE = 128 * VS;
;     LAS bf16_t* L = (LAS bf16_t*)lds;
;     __syncthreads();
; #pragma unroll
;     for (int k = 0; k < 2; ++k) {
;         const int it = it0 + k, bh = it >> 5, n = it & 31, b = bh >> 3, h = bh & 7; const long r0 = (long)b * SEQ + n * 128;
;         stage_T<128, 128, VS>(L + (2 * k) * TILE, RK, r0, 1024, h * 128, 0, tid);
;         stage_T<128, 128, VS>(L + (2 * k + 1) * TILE, RV, r0, 1024, h * 128, 0, tid);
;     }
;     __syncthreads();
.LBB0_1036:
	s_or_b64 exec, exec, s[0:1]
	s_waitcnt vmcnt(0)
	ds_write_b16 v69, v18
	ds_write_b16_d16_hi v69, v18 offset:272
	ds_write_b16 v69, v19 offset:544
	ds_write_b16_d16_hi v69, v19 offset:816
	ds_write_b16 v69, v20 offset:1088
	ds_write_b16_d16_hi v69, v20 offset:1360
	ds_write_b16 v69, v21 offset:1632
	ds_write_b16_d16_hi v69, v21 offset:1904
	ds_write_b16 v71, v22
	ds_write_b16_d16_hi v71, v22 offset:272
	ds_write_b16 v71, v23 offset:544
	ds_write_b16_d16_hi v71, v23 offset:816
	ds_write_b16 v71, v24 offset:1088
	ds_write_b16_d16_hi v71, v24 offset:1360
	ds_write_b16 v71, v25 offset:1632
	ds_write_b16_d16_hi v71, v25 offset:1904
	ds_write_b16 v73, v26
	ds_write_b16_d16_hi v73, v26 offset:272
	ds_write_b16 v73, v27 offset:544
	ds_write_b16_d16_hi v73, v27 offset:816
	ds_write_b16 v73, v28 offset:1088
	ds_write_b16_d16_hi v73, v28 offset:1360
	ds_write_b16 v73, v29 offset:1632
	ds_write_b16_d16_hi v73, v29 offset:1904
	ds_write_b16 v80, v30
	ds_write_b16_d16_hi v80, v30 offset:272
	ds_write_b16 v80, v31 offset:544
	ds_write_b16_d16_hi v80, v31 offset:816
	ds_write_b16 v80, v32 offset:1088
	ds_write_b16_d16_hi v80, v32 offset:1360
	ds_write_b16 v80, v33 offset:1632
	ds_write_b16_d16_hi v80, v33 offset:1904
	ds_write_b16 v69, v34 offset:34816
	ds_write_b16_d16_hi v69, v34 offset:35088
	ds_write_b16 v69, v35 offset:35360
	ds_write_b16_d16_hi v69, v35 offset:35632
	ds_write_b16 v69, v36 offset:35904
	ds_write_b16_d16_hi v69, v36 offset:36176
	ds_write_b16 v69, v37 offset:36448
	ds_write_b16_d16_hi v69, v37 offset:36720
	ds_write_b16 v71, v38 offset:34816
	ds_write_b16_d16_hi v71, v38 offset:35088
	ds_write_b16 v71, v39 offset:35360
	ds_write_b16_d16_hi v71, v39 offset:35632
	ds_write_b16 v71, v40 offset:35904
	ds_write_b16_d16_hi v71, v40 offset:36176
	ds_write_b16 v71, v41 offset:36448
	ds_write_b16_d16_hi v71, v41 offset:36720
	ds_write_b16 v73, v42 offset:34816
	ds_write_b16_d16_hi v73, v42 offset:35088
	ds_write_b16 v73, v43 offset:35360
	ds_write_b16_d16_hi v73, v43 offset:35632
	ds_write_b16 v73, v44 offset:35904
	ds_write_b16_d16_hi v73, v44 offset:36176
	ds_write_b16 v73, v45 offset:36448
	ds_write_b16_d16_hi v73, v45 offset:36720
	ds_write_b16 v80, v46 offset:34816
	ds_write_b16_d16_hi v80, v46 offset:35088
	ds_write_b16 v80, v47 offset:35360
	ds_write_b16_d16_hi v80, v47 offset:35632
	ds_write_b16 v80, v48 offset:35904
	ds_write_b16_d16_hi v80, v48 offset:36176
	ds_write_b16 v80, v49 offset:36448
	ds_write_b16_d16_hi v80, v49 offset:36720
	ds_write_b16 v81, v50
	ds_write_b16_d16_hi v81, v50 offset:272
	ds_write_b16 v81, v51 offset:544
	ds_write_b16_d16_hi v81, v51 offset:816
	ds_write_b16 v81, v52 offset:1088
	ds_write_b16_d16_hi v81, v52 offset:1360
	ds_write_b16 v81, v53 offset:1632
	ds_write_b16_d16_hi v81, v53 offset:1904
	ds_write_b16 v82, v54
	ds_write_b16_d16_hi v82, v54 offset:272
	ds_write_b16 v82, v55 offset:544
	ds_write_b16_d16_hi v82, v55 offset:816
	ds_write_b16 v82, v56 offset:1088
	ds_write_b16_d16_hi v82, v56 offset:1360
	ds_write_b16 v82, v57 offset:1632
	ds_write_b16_d16_hi v82, v57 offset:1904
	ds_write_b16 v83, v58
	ds_write_b16_d16_hi v83, v58 offset:272
	ds_write_b16 v83, v59 offset:544
	ds_write_b16_d16_hi v83, v59 offset:816
	ds_write_b16 v83, v60 offset:1088
	ds_write_b16_d16_hi v83, v60 offset:1360
	ds_write_b16 v83, v61 offset:1632
	ds_write_b16_d16_hi v83, v61 offset:1904
	ds_write_b16 v84, v62
	ds_write_b16_d16_hi v84, v62 offset:272
	ds_write_b16 v84, v63 offset:544
	ds_write_b16_d16_hi v84, v63 offset:816
	ds_write_b16 v84, v64 offset:1088
	ds_write_b16_d16_hi v84, v64 offset:1360
	ds_write_b16 v84, v65 offset:1632
	ds_write_b16_d16_hi v84, v65 offset:1904
	ds_write_b16 v85, v236
	ds_write_b16_d16_hi v85, v236 offset:272
	ds_write_b16 v85, v237 offset:544
	ds_write_b16_d16_hi v85, v237 offset:816
	ds_write_b16 v85, v238 offset:1088
	ds_write_b16_d16_hi v85, v238 offset:1360
	ds_write_b16 v85, v239 offset:1632
	ds_write_b16_d16_hi v85, v239 offset:1904
	ds_write_b16 v87, v240
	ds_write_b16_d16_hi v87, v240 offset:272
	ds_write_b16 v87, v241 offset:544
	ds_write_b16_d16_hi v87, v241 offset:816
	ds_write_b16 v87, v242 offset:1088
	ds_write_b16_d16_hi v87, v242 offset:1360
	ds_write_b16 v87, v243 offset:1632
	ds_write_b16_d16_hi v87, v243 offset:1904
	ds_write_b16 v88, v244
	ds_write_b16_d16_hi v88, v244 offset:272
	ds_write_b16 v88, v245 offset:544
	ds_write_b16_d16_hi v88, v245 offset:816
	ds_write_b16 v88, v246 offset:1088
	ds_write_b16_d16_hi v88, v246 offset:1360
	ds_write_b16 v88, v247 offset:1632
	ds_write_b16_d16_hi v88, v247 offset:1904
	ds_write_b16 v89, v248
	ds_write_b16_d16_hi v89, v248 offset:272
	ds_write_b16 v89, v249 offset:544
	ds_write_b16_d16_hi v89, v249 offset:816
	ds_write_b16 v89, v250 offset:1088
	ds_write_b16_d16_hi v89, v250 offset:1360
	ds_write_b16 v89, v251 offset:1632
	ds_write_b16_d16_hi v89, v251 offset:1904
	s_waitcnt lgkmcnt(0)
	s_barrier
; #define LAS __attribute__((address_space(3)))
; __device__ __forceinline__ int crow(int r, int hi) { return (r & 3) + 8 * (r >> 2) + 4 * hi; }
; __device__ __forceinline__ float lg2gamma(int h) { return log2f(1.0f - exp2f(-5.0f - (float)h)); }
; #define MFMA32(a, b, c) __builtin_amdgcn_mfma_f32_32x32x16_bf16((a), (b), (c), 0, 0, 0)
; __device__ __forceinline__ void kv_item2(int it0, LAS unsigned char* lds, const bf16_t* RK, const bf16_t* RV, float* STATE, int tid, int wid, int lane) {
;     ...
;     const int half = wid >> 2, it = it0 + half, h = (it >> 5) & 7;
;     const LAS bf16_t* KT = L + (2 * half) * TILE; const LAS bf16_t* VT = KT + TILE;
;     const int x = lane & 31, hi = lane >> 5, et = wid & 3;
;     f32x16 acc[4];
; #pragma unroll
;     for (int dt = 0; dt < 4; ++dt) acc[dt] = f32x16{};
; #pragma unroll
;     for (int ks = 0; ks < 8; ++ks) {
;         const int ea = 32 * et + x, cc = 16 * ks + 8 * hi;
;         const bf16x8 A = *(const LAS bf16x8*)(VT + ea * VS + swzc(ea, cc));
; #pragma unroll
;         for (int dt = 0; dt < 4; ++dt) { const int da = 32 * dt + x; acc[dt] = MFMA32(A, *(const LAS bf16x8*)(KT + da * VS + swzc(da, cc)), acc[dt]); }
;     }
;     const float g127 = exp2f(127.0f * lg2gamma(h));
;     float* sp = STATE + (size_t)it * 16384;
; #pragma unroll
;     for (int dt = 0; dt < 4; ++dt)
; #pragma unroll
;         for (int r = 0; r < 16; ++r) sp[(32 * et + crow(r, hi)) * 128 + 32 * dt + x] = acc[dt][r] * g127;
	ds_read_b128 v[2:5], v90 offset:34816
	ds_read_b128 v[6:9], v92
	s_waitcnt lgkmcnt(0)
	v_mfma_f32_32x32x16_bf16 v[50:65], v[2:5], v[6:9], 0
	ds_read_b128 v[6:9], v93
	ds_read_b128 v[10:13], v94
	s_add_i32 s0, s33, s8
	s_bfe_u32 s1, s0, 0x30005
	v_cvt_f32_ubyte0_e32 v133, s1
	v_sub_f32_e32 v133, 0xc0a00000, v133
	v_cmp_gt_f32_e32 vcc, s14, v133
	s_and_b64 s[2:3], vcc, exec
	s_waitcnt lgkmcnt(1)
	v_mfma_f32_32x32x16_bf16 v[34:49], v[2:5], v[6:9], 0
	ds_read_b128 v[6:9], v95
	ds_read_b128 v[134:137], v96 offset:34816
	ds_read_b128 v[138:141], v97
	ds_read_b128 v[142:145], v98
	v_cndmask_b32_e32 v188, 0, v91, vcc
	v_add_f32_e32 v133, v133, v188
	v_exp_f32_e32 v133, v133
	s_cselect_b32 s1, 0xffffffc0, 0
	v_ldexp_f32 v133, v133, s1
	s_waitcnt lgkmcnt(4)
	v_mfma_f32_32x32x16_bf16 v[18:33], v[2:5], v[10:13], 0
	v_sub_f32_e32 v133, 1.0, v133
	v_cmp_gt_f32_e32 vcc, s15, v133
	s_and_b64 s[2:3], vcc, exec
	s_cselect_b32 s1, 32, 0
	v_ldexp_f32 v133, v133, s1
	v_log_f32_e32 v133, v133
	v_cndmask_b32_e32 v188, 0, v132, vcc
	s_waitcnt lgkmcnt(3)
	v_mfma_f32_32x32x16_bf16 v[2:17], v[2:5], v[6:9], 0
	v_sub_f32_e32 v133, v133, v188
	v_mul_f32_e32 v188, 0x42fe0000, v133
	v_cmp_gt_f32_e32 vcc, s14, v188
	s_and_b64 s[2:3], vcc, exec
	s_cselect_b32 s1, 0xffffffc0, 0
	v_cndmask_b32_e32 v188, 0, v91, vcc
	s_waitcnt lgkmcnt(1)
	v_mfma_f32_32x32x16_bf16 v[50:65], v[134:137], v[138:141], v[50:65]
	v_fmac_f32_e32 v188, 0x42fe0000, v133
	v_exp_f32_e32 v133, v188
	s_add_i32 s8, s8, s9
	s_add_i32 s10, s10, s11
	s_add_i32 s12, s12, s13
	v_ldexp_f32 v133, v133, s1
	s_ashr_i32 s1, s0, 31
	s_waitcnt lgkmcnt(0)
	v_mfma_f32_32x32x16_bf16 v[34:49], v[134:137], v[142:145], v[34:49]
	ds_read_b128 v[138:141], v99
	ds_read_b128 v[142:145], v100
	s_lshl_b64 s[0:1], s[0:1], 16
	s_cmpk_lt_i32 s8, 0x200
	s_waitcnt lgkmcnt(1)
	v_mfma_f32_32x32x16_bf16 v[18:33], v[134:137], v[138:141], v[18:33]
	s_waitcnt lgkmcnt(0)
	v_mfma_f32_32x32x16_bf16 v[2:17], v[134:137], v[142:145], v[2:17]
	ds_read_b128 v[134:137], v101 offset:34816
	ds_read_b128 v[138:141], v103
	s_waitcnt lgkmcnt(0)
	v_mfma_f32_32x32x16_bf16 v[50:65], v[134:137], v[138:141], v[50:65]
	ds_read_b128 v[138:141], v104
	ds_read_b128 v[142:145], v105
	ds_read_b128 v[146:149], v106
	ds_read_b128 v[152:155], v107 offset:34816
	ds_read_b128 v[156:159], v108
	ds_read_b128 v[160:163], v109
	s_waitcnt lgkmcnt(5)
	v_mfma_f32_32x32x16_bf16 v[34:49], v[134:137], v[138:141], v[34:49]
	ds_read_b128 v[138:141], v110
	ds_read_b128 v[164:167], v111
	ds_read_b128 v[168:171], v112 offset:34816
	ds_read_b128 v[172:175], v113
	ds_read_b128 v[176:179], v114
	ds_read_b128 v[180:183], v115
	ds_read_b128 v[184:187], v116
	ds_read_b128 v[192:195], v117 offset:34816
	s_waitcnt lgkmcnt(12)
	v_mfma_f32_32x32x16_bf16 v[18:33], v[134:137], v[142:145], v[18:33]
	ds_read_b128 v[142:145], v118
	ds_read_b128 v[196:199], v119
	ds_read_b128 v[200:203], v120
	ds_read_b128 v[204:207], v121
	ds_read_b128 v[208:211], v122 offset:34816
	ds_read_b128 v[212:215], v124
	ds_read_b128 v[216:219], v125
	ds_read_b128 v[220:223], v126
	s_waitcnt lgkmcnt(14)
	v_mfma_f32_32x32x16_bf16 v[2:17], v[134:137], v[146:149], v[2:17]
	v_mfma_f32_32x32x16_bf16 v[50:65], v[152:155], v[156:159], v[50:65]
	ds_read_b128 v[156:159], v127
	ds_read_b128 v[224:227], v102 offset:34816
	v_mfma_f32_32x32x16_bf16 v[34:49], v[152:155], v[160:163], v[34:49]
	v_mfma_f32_32x32x16_bf16 v[18:33], v[152:155], v[138:141], v[18:33]
	v_mfma_f32_32x32x16_bf16 v[2:17], v[152:155], v[164:167], v[2:17]
	s_waitcnt lgkmcnt(14)
	v_mfma_f32_32x32x16_bf16 v[50:65], v[168:171], v[172:175], v[50:65]
	ds_read_b128 v[172:175], v128
	ds_read_b128 v[228:231], v130
	s_waitcnt lgkmcnt(14)
	v_mfma_f32_32x32x16_bf16 v[34:49], v[168:171], v[176:179], v[34:49]
	v_mfma_f32_32x32x16_bf16 v[18:33], v[168:171], v[180:183], v[18:33]
	s_waitcnt lgkmcnt(13)
	v_mfma_f32_32x32x16_bf16 v[2:17], v[168:171], v[184:187], v[2:17]
	s_waitcnt lgkmcnt(11)
	v_mfma_f32_32x32x16_bf16 v[50:65], v[192:195], v[142:145], v[50:65]
	ds_read_b128 v[142:145], v131
	ds_read_b128 v[232:235], v86
	s_waitcnt lgkmcnt(12)
	v_mfma_f32_32x32x16_bf16 v[34:49], v[192:195], v[196:199], v[34:49]
	s_waitcnt lgkmcnt(11)
	v_mfma_f32_32x32x16_bf16 v[18:33], v[192:195], v[200:203], v[18:33]
	s_waitcnt lgkmcnt(10)
	v_mfma_f32_32x32x16_bf16 v[2:17], v[192:195], v[204:207], v[2:17]
	s_waitcnt lgkmcnt(8)
	v_mfma_f32_32x32x16_bf16 v[50:65], v[208:211], v[212:215], v[50:65]
	s_waitcnt lgkmcnt(7)
	v_mfma_f32_32x32x16_bf16 v[34:49], v[208:211], v[216:219], v[34:49]
	s_waitcnt lgkmcnt(6)
	v_mfma_f32_32x32x16_bf16 v[18:33], v[208:211], v[220:223], v[18:33]
	s_waitcnt lgkmcnt(5)
	v_mfma_f32_32x32x16_bf16 v[2:17], v[208:211], v[156:159], v[2:17]
	s_waitcnt lgkmcnt(3)
	v_mfma_f32_32x32x16_bf16 v[50:65], v[224:227], v[172:175], v[50:65]
	v_lshl_add_u64 v[172:173], v[78:79], 0, s[0:1]
	s_waitcnt lgkmcnt(2)
	v_mfma_f32_32x32x16_bf16 v[34:49], v[224:227], v[228:231], v[34:49]
	s_nop 8
	v_mul_f32_e32 v50, v133, v50
	global_store_dword v[172:173], v50, off
	v_mul_f32_e32 v50, v133, v51
	global_store_dword v[172:173], v50, off offset:512
	v_mul_f32_e32 v50, v133, v52
	global_store_dword v[172:173], v50, off offset:1024
	v_mul_f32_e32 v50, v133, v53
	s_waitcnt lgkmcnt(1)
	v_mfma_f32_32x32x16_bf16 v[18:33], v[224:227], v[142:145], v[18:33]
	global_store_dword v[172:173], v50, off offset:1536
	v_add_co_u32_e32 v50, vcc, s16, v172
	v_mul_f32_e32 v34, v133, v34
	s_nop 0
	v_addc_co_u32_e32 v51, vcc, 0, v173, vcc
	global_store_dword v[172:173], v34, off offset:128
	s_waitcnt lgkmcnt(0)
; __device__ __forceinline__ int crow(int r, int hi) { return (r & 3) + 8 * (r >> 2) + 4 * hi; }
; __device__ __forceinline__ float lg2gamma(int h) { return log2f(1.0f - exp2f(-5.0f - (float)h)); }
; __device__ __forceinline__ void kv_item2(int it0, LAS unsigned char* lds, const bf16_t* RK, const bf16_t* RV, float* STATE, int tid, int wid, int lane) {
;     ...
;     __syncthreads();
; #pragma unroll
;     for (int k = 0; k < 2; ++k) {
;         const int it = it0 + k, bh = it >> 5, n = it & 31, b = bh >> 3, h = bh & 7; const long r0 = (long)b * SEQ + n * 128;
;         stage_T<128, 128, VS>(L + (2 * k) * TILE, RK, r0, 1024, h * 128, 0, tid);
;         stage_T<128, 128, VS>(L + (2 * k + 1) * TILE, RV, r0, 1024, h * 128, 0, tid);
;     ...
;     const float g127 = exp2f(127.0f * lg2gamma(h));
;     float* sp = STATE + (size_t)it * 16384;
; #pragma unroll
;     for (int dt = 0; dt < 4; ++dt)
; #pragma unroll
;         for (int r = 0; r < 16; ++r) sp[(32 * et + crow(r, hi)) * 128 + 32 * dt + x] = acc[dt][r] * g127;
	v_mfma_f32_32x32x16_bf16 v[2:17], v[224:227], v[232:235], v[2:17]
	s_nop 3
	v_mul_f32_e32 v18, v133, v18
	v_mul_f32_e32 v34, v133, v35
	global_store_dword v[172:173], v18, off offset:256
	v_mul_f32_e32 v18, v133, v19
	v_add_co_u32_e32 v52, vcc, s17, v172
	global_store_dword v[172:173], v34, off offset:640
	s_nop 1
	v_mul_f32_e32 v2, v133, v2
	global_store_dword v[172:173], v2, off offset:384
	v_mul_f32_e32 v2, v133, v3
	v_mul_f32_e32 v34, v133, v36
	global_store_dword v[172:173], v18, off offset:768
	v_mul_f32_e32 v18, v133, v20
	global_store_dword v[172:173], v2, off offset:896
	v_mul_f32_e32 v2, v133, v4
	v_mul_f32_e32 v54, v133, v54
	v_addc_co_u32_e32 v53, vcc, 0, v173, vcc
	global_store_dword v[172:173], v34, off offset:1152
	v_mul_f32_e32 v34, v133, v37
	global_store_dword v[172:173], v18, off offset:1280
	v_mul_f32_e32 v18, v133, v21
	global_store_dword v[172:173], v2, off offset:1408
	v_mul_f32_e32 v2, v133, v5
	global_store_dword v[52:53], v54, off offset:-4096
	v_mul_f32_e32 v54, v133, v55
	global_store_dword v[172:173], v34, off offset:1664
	v_mul_f32_e32 v34, v133, v38
	global_store_dword v[172:173], v18, off offset:1792
	v_mul_f32_e32 v18, v133, v22
	global_store_dword v[172:173], v2, off offset:1920
	v_mul_f32_e32 v2, v133, v6
	global_store_dword v[50:51], v54, off offset:512
	v_mul_f32_e32 v54, v133, v56
	global_store_dword v[50:51], v34, off offset:128
	v_mul_f32_e32 v34, v133, v39
	global_store_dword v[50:51], v18, off offset:256
	v_mul_f32_e32 v18, v133, v23
	global_store_dword v[50:51], v2, off offset:384
	v_mul_f32_e32 v2, v133, v7
	global_store_dword v[50:51], v54, off offset:1024
	v_mul_f32_e32 v54, v133, v57
	global_store_dword v[50:51], v34, off offset:640
	v_mul_f32_e32 v34, v133, v40
	global_store_dword v[50:51], v18, off offset:768
	v_mul_f32_e32 v18, v133, v24
	global_store_dword v[50:51], v2, off offset:896
	v_mul_f32_e32 v2, v133, v8
	global_store_dword v[50:51], v54, off offset:1536
	v_mul_f32_e32 v54, v133, v58
	global_store_dword v[50:51], v34, off offset:1152
	v_mul_f32_e32 v34, v133, v41
	global_store_dword v[50:51], v18, off offset:1280
	v_mul_f32_e32 v18, v133, v25
	global_store_dword v[50:51], v2, off offset:1408
	v_mul_f32_e32 v2, v133, v9
	global_store_dword v[52:53], v54, off
	v_mul_f32_e32 v54, v133, v59
	global_store_dword v[50:51], v34, off offset:1664
	v_mul_f32_e32 v34, v133, v42
	global_store_dword v[50:51], v18, off offset:1792
	v_mul_f32_e32 v18, v133, v26
	global_store_dword v[50:51], v2, off offset:1920
	v_mul_f32_e32 v2, v133, v10
	global_store_dword v[52:53], v54, off offset:512
	v_mul_f32_e32 v54, v133, v60
	global_store_dword v[52:53], v34, off offset:128
	v_mul_f32_e32 v34, v133, v43
	global_store_dword v[52:53], v18, off offset:256
	v_mul_f32_e32 v18, v133, v27
	global_store_dword v[52:53], v2, off offset:384
	v_mul_f32_e32 v2, v133, v11
	global_store_dword v[52:53], v54, off offset:1024
	v_mul_f32_e32 v54, v133, v61
	global_store_dword v[52:53], v34, off offset:640
	v_mul_f32_e32 v34, v133, v44
	global_store_dword v[52:53], v18, off offset:768
	v_mul_f32_e32 v18, v133, v28
	global_store_dword v[52:53], v2, off offset:896
	v_mul_f32_e32 v2, v133, v12
	global_store_dword v[52:53], v54, off offset:1536
	v_add_co_u32_e32 v54, vcc, s18, v172
	global_store_dword v[52:53], v34, off offset:1152
	v_mul_f32_e32 v34, v133, v45
	global_store_dword v[52:53], v18, off offset:1280
	v_mul_f32_e32 v18, v133, v29
	global_store_dword v[52:53], v2, off offset:1408
	v_mul_f32_e32 v2, v133, v13
	v_mul_f32_e32 v56, v133, v62
	v_addc_co_u32_e32 v55, vcc, 0, v173, vcc
	global_store_dword v[52:53], v34, off offset:1664
	v_mul_f32_e32 v34, v133, v46
	global_store_dword v[52:53], v18, off offset:1792
	v_mul_f32_e32 v18, v133, v30
	global_store_dword v[52:53], v2, off offset:1920
	v_mul_f32_e32 v2, v133, v14
	global_store_dword v[54:55], v56, off
	v_mul_f32_e32 v56, v133, v63
	global_store_dword v[54:55], v34, off offset:128
	v_mul_f32_e32 v34, v133, v47
	global_store_dword v[54:55], v18, off offset:256
	v_mul_f32_e32 v18, v133, v31
	global_store_dword v[54:55], v2, off offset:384
	v_mul_f32_e32 v2, v133, v15
	global_store_dword v[54:55], v56, off offset:512
	v_mul_f32_e32 v56, v133, v64
	global_store_dword v[54:55], v34, off offset:640
	v_mul_f32_e32 v34, v133, v48
	global_store_dword v[54:55], v18, off offset:768
	v_mul_f32_e32 v18, v133, v32
	global_store_dword v[54:55], v2, off offset:896
	v_mul_f32_e32 v2, v133, v16
	global_store_dword v[54:55], v56, off offset:1024
	v_mul_f32_e32 v56, v133, v65
	global_store_dword v[54:55], v34, off offset:1152
	v_mul_f32_e32 v34, v133, v49
	global_store_dword v[54:55], v18, off offset:1280
	v_mul_f32_e32 v18, v133, v33
	global_store_dword v[54:55], v2, off offset:1408
	v_mul_f32_e32 v2, v133, v17
	global_store_dword v[54:55], v56, off offset:1536
	global_store_dword v[54:55], v34, off offset:1664
	global_store_dword v[54:55], v18, off offset:1792
	global_store_dword v[54:55], v2, off offset:1920
	s_cbranch_scc0 .LBB0_1083
.LBB0_1037:
	s_ashr_i32 s0, s8, 8
	s_ashr_i32 s1, s0, 31
	s_lshl_b64 s[2:3], s[0:1], 12
	s_and_b32 s1, s10, 0xf00
	s_or_b32 s2, s2, s1
	s_and_b32 s1, s12, 0x380
	s_lshl_b32 s4, s1, 1
	v_mov_b32_e32 v3, s3
	v_or_b32_e32 v2, s2, v68
	s_cmp_gt_i32 s0, -1
	v_lshl_add_u64 v[6:7], v[66:67], 0, s[4:5]
	s_cselect_b64 s[6:7], -1, 0
	s_cmp_lt_i32 s0, 0
	v_lshlrev_b64 v[10:11], 11, v[2:3]
	s_barrier
	s_cbranch_scc1 .LBB0_1039
	v_lshl_add_u64 v[2:3], v[6:7], 0, v[10:11]
	global_load_dwordx4 v[18:21], v[2:3], off
	s_branch .LBB0_1040
; #define LAS __attribute__((address_space(3)))
; template <int NROWS, int NCOLS, int VS>
; __device__ __forceinline__ void stage_T(LAS bf16_t* dstT, const bf16_t* src, long r0, int ld, int col0, long rmin, int tid) {
;     constexpr int NCH = NCOLS / 8, TOT = NROWS * NCH;
; #pragma unroll
;     for (int i = 0; i < TOT / 512; ++i) {
;         const int idx = tid + 512 * i;
;         int ch, j;
;         if (NCH == 16) { ch = (idx & 7) + 8 * ((idx >> 6) & 1); j = ((idx >> 3) & 7) + 8 * (idx >> 7); } else { ch = idx & 7; j = idx >> 3; }
;         const long r = r0 + j;
;         u32x4 v = {0u, 0u, 0u, 0u};
;         if (r >= rmin) v = STG_NT ? __builtin_nontemporal_load((const u32x4*)(src + r * ld + col0 + 8 * ch)) : *(const u32x4*)(src + r * ld + col0 + 8 * ch);
;         LAS bf16_t* d = dstT + (8 * ch) * VS + (j ^ ((ch & 15) << 3));
;         d[0 * VS] = (bf16_t)(v.x & 0xffffu); d[1 * VS] = (bf16_t)(v.x >> 16); d[2 * VS] = (bf16_t)(v.y & 0xffffu); d[3 * VS] = (bf16_t)(v.y >> 16);
;         d[4 * VS] = (bf16_t)(v.z & 0xffffu); d[5 * VS] = (bf16_t)(v.z >> 16); d[6 * VS] = (bf16_t)(v.w & 0xffffu); d[7 * VS] = (bf16_t)(v.w >> 16);
;     }
; }
; __device__ __forceinline__ void kv_item2(int it0, LAS unsigned char* lds, const bf16_t* RK, const bf16_t* RV, float* STATE, int tid, int wid, int lane) {
;     ...
;     for (int k = 0; k < 2; ++k) {
;         const int it = it0 + k, bh = it >> 5, n = it & 31, b = bh >> 3, h = bh & 7; const long r0 = (long)b * SEQ + n * 128;
;         stage_T<128, 128, VS>(L + (2 * k) * TILE, RK, r0, 1024, h * 128, 0, tid);
;         stage_T<128, 128, VS>(L + (2 * k + 1) * TILE, RV, r0, 1024, h * 128, 0, tid);
.LBB0_1039:
	v_mov_b32_e32 v18, 0
	v_mov_b32_e32 v19, 0
	v_mov_b32_e32 v20, 0
	v_mov_b32_e32 v21, 0
.LBB0_1040:
	v_mov_b32_e32 v3, s3
	v_or_b32_e32 v2, s2, v70
	v_cndmask_b32_e64 v4, 0, 1, s[6:7]
	v_cmp_ne_u32_e64 s[0:1], 1, v4
	s_andn2_b64 vcc, exec, s[6:7]
	v_lshlrev_b64 v[12:13], 11, v[2:3]
	s_cbranch_vccnz .LBB0_1042
	v_lshl_add_u64 v[2:3], v[6:7], 0, v[12:13]
	global_load_dwordx4 v[22:25], v[2:3], off
	s_branch .LBB0_1043
.LBB0_1042:
	v_mov_b32_e32 v22, 0
	v_mov_b32_e32 v23, 0
	v_mov_b32_e32 v24, 0
	v_mov_b32_e32 v25, 0
.LBB0_1043:
	v_mov_b32_e32 v3, s3
	v_or_b32_e32 v2, s2, v72
	s_and_b64 vcc, exec, s[0:1]
	v_lshlrev_b64 v[14:15], 11, v[2:3]
	s_cbranch_vccnz .LBB0_1045
	v_lshl_add_u64 v[2:3], v[6:7], 0, v[14:15]
	global_load_dwordx4 v[26:29], v[2:3], off
	s_branch .LBB0_1046
.LBB0_1045:
	v_mov_b32_e32 v26, 0
	v_mov_b32_e32 v27, 0
	v_mov_b32_e32 v28, 0
	v_mov_b32_e32 v29, 0
.LBB0_1046:
	v_mov_b32_e32 v3, s3
	v_or_b32_e32 v2, s2, v74
	s_and_b64 vcc, exec, s[0:1]
	v_lshlrev_b64 v[16:17], 11, v[2:3]
	s_cbranch_vccnz .LBB0_1048
	v_lshl_add_u64 v[2:3], v[6:7], 0, v[16:17]
	global_load_dwordx4 v[30:33], v[2:3], off
	s_branch .LBB0_1049
.LBB0_1048:
	v_mov_b32_e32 v30, 0
	v_mov_b32_e32 v31, 0
	v_mov_b32_e32 v32, 0
	v_mov_b32_e32 v33, 0
.LBB0_1049:
	s_and_b64 vcc, exec, s[0:1]
	v_lshl_add_u64 v[8:9], v[76:77], 0, s[4:5]
	s_cbranch_vccnz .LBB0_1051
	v_lshl_add_u64 v[2:3], v[8:9], 0, v[10:11]
	global_load_dwordx4 v[34:37], v[2:3], off
	s_branch .LBB0_1052
.LBB0_1051:
	v_mov_b32_e32 v34, 0
	v_mov_b32_e32 v35, 0
	v_mov_b32_e32 v36, 0
	v_mov_b32_e32 v37, 0
.LBB0_1052:
	s_and_b64 vcc, exec, s[0:1]
	s_cbranch_vccnz .LBB0_1054
	v_lshl_add_u64 v[2:3], v[8:9], 0, v[12:13]
	global_load_dwordx4 v[38:41], v[2:3], off
	s_branch .LBB0_1055
.LBB0_1054:
	v_mov_b32_e32 v38, 0
	v_mov_b32_e32 v39, 0
	v_mov_b32_e32 v40, 0
	v_mov_b32_e32 v41, 0
.LBB0_1055:
	s_and_b64 vcc, exec, s[0:1]
	s_cbranch_vccnz .LBB0_1057
	v_lshl_add_u64 v[2:3], v[8:9], 0, v[14:15]
	global_load_dwordx4 v[42:45], v[2:3], off
	s_branch .LBB0_1058
.LBB0_1057:
	v_mov_b32_e32 v42, 0
	v_mov_b32_e32 v43, 0
	v_mov_b32_e32 v44, 0
	v_mov_b32_e32 v45, 0
.LBB0_1058:
	s_and_b64 vcc, exec, s[0:1]
	s_cbranch_vccnz .LBB0_1060
	v_lshl_add_u64 v[2:3], v[8:9], 0, v[16:17]
	global_load_dwordx4 v[46:49], v[2:3], off
	s_branch .LBB0_1061
.LBB0_1060:
	v_mov_b32_e32 v46, 0
	v_mov_b32_e32 v47, 0
	v_mov_b32_e32 v48, 0
	v_mov_b32_e32 v49, 0
.LBB0_1061:
	s_bitset1_b32 s2, 7
	v_mov_b32_e32 v3, s3
	v_or_b32_e32 v2, s2, v68
	s_and_b64 vcc, exec, s[0:1]
	v_lshlrev_b64 v[10:11], 11, v[2:3]
	s_cbranch_vccnz .LBB0_1063
	v_lshl_add_u64 v[2:3], v[6:7], 0, v[10:11]
	global_load_dwordx4 v[50:53], v[2:3], off
	s_branch .LBB0_1064
.LBB0_1063:
	v_mov_b32_e32 v50, 0
	v_mov_b32_e32 v51, 0
	v_mov_b32_e32 v52, 0
	v_mov_b32_e32 v53, 0
.LBB0_1064:
	v_mov_b32_e32 v3, s3
	v_or_b32_e32 v2, s2, v70
	s_and_b64 vcc, exec, s[0:1]
	v_lshlrev_b64 v[14:15], 11, v[2:3]
	s_cbranch_vccnz .LBB0_1066
	v_lshl_add_u64 v[2:3], v[6:7], 0, v[14:15]
	global_load_dwordx4 v[54:57], v[2:3], off
	s_branch .LBB0_1067
.LBB0_1066:
	v_mov_b32_e32 v54, 0
	v_mov_b32_e32 v55, 0
	v_mov_b32_e32 v56, 0
	v_mov_b32_e32 v57, 0
.LBB0_1067:
	v_mov_b32_e32 v3, s3
	v_or_b32_e32 v2, s2, v72
	s_and_b64 vcc, exec, s[0:1]
	v_lshlrev_b64 v[16:17], 11, v[2:3]
	s_cbranch_vccnz .LBB0_1069
	v_lshl_add_u64 v[2:3], v[6:7], 0, v[16:17]
	global_load_dwordx4 v[58:61], v[2:3], off
	s_branch .LBB0_1070
.LBB0_1069:
	v_mov_b32_e32 v58, 0
	v_mov_b32_e32 v59, 0
	v_mov_b32_e32 v60, 0
	v_mov_b32_e32 v61, 0
.LBB0_1070:
	v_lshl_add_u64 v[4:5], s[2:3], 0, v[74:75]
	v_cmp_lt_i64_e64 s[2:3], -1, v[4:5]
	v_mov_b32_e32 v62, 0
	v_lshlrev_b64 v[12:13], 11, v[4:5]
	v_mov_b32_e32 v63, 0
	v_mov_b32_e32 v64, 0
	v_mov_b32_e32 v65, 0
	s_and_saveexec_b64 s[6:7], s[2:3]
	s_cbranch_execz .LBB0_1072
	v_lshl_add_u64 v[2:3], v[6:7], 0, v[12:13]
	global_load_dwordx4 v[62:65], v[2:3], off
.LBB0_1072:
	s_or_b64 exec, exec, s[6:7]
	s_and_b64 vcc, exec, s[0:1]
	s_cbranch_vccnz .LBB0_1074
	v_lshl_add_u64 v[2:3], v[8:9], 0, v[10:11]
	global_load_dwordx4 v[236:239], v[2:3], off
	s_branch .LBB0_1075
.LBB0_1074:
	v_mov_b32_e32 v236, 0
	v_mov_b32_e32 v237, 0
	v_mov_b32_e32 v238, 0
	v_mov_b32_e32 v239, 0
.LBB0_1075:
	s_and_b64 vcc, exec, s[0:1]
	s_cbranch_vccnz .LBB0_1077
	v_lshl_add_u64 v[2:3], v[8:9], 0, v[14:15]
	global_load_dwordx4 v[240:243], v[2:3], off
	s_branch .LBB0_1078
.LBB0_1077:
	v_mov_b32_e32 v240, 0
	v_mov_b32_e32 v241, 0
	v_mov_b32_e32 v242, 0
	v_mov_b32_e32 v243, 0
.LBB0_1078:
	s_and_b64 vcc, exec, s[0:1]
	s_cbranch_vccnz .LBB0_1080
	v_lshl_add_u64 v[2:3], v[8:9], 0, v[16:17]
	global_load_dwordx4 v[244:247], v[2:3], off
	s_branch .LBB0_1081
.LBB0_1080:
	v_mov_b32_e32 v244, 0
	v_mov_b32_e32 v245, 0
	v_mov_b32_e32 v246, 0
	v_mov_b32_e32 v247, 0
.LBB0_1081:
	v_mov_b32_e32 v248, 0
	v_mov_b32_e32 v249, 0
	v_mov_b32_e32 v250, 0
	v_mov_b32_e32 v251, 0
	s_and_saveexec_b64 s[0:1], s[2:3]
	s_cbranch_execz .LBB0_1036
	v_lshl_add_u64 v[2:3], v[8:9], 0, v[12:13]
	global_load_dwordx4 v[248:251], v[2:3], off
	s_branch .LBB0_1036

; #define LAS __attribute__((address_space(3)))
; template <int NROWS, int NCOLS, int VS>
; __device__ __forceinline__ void stage_T(LAS bf16_t* dstT, const bf16_t* src, long r0, int ld, int col0, long rmin, int tid) {
;     constexpr int NCH = NCOLS / 8, TOT = NROWS * NCH;
; #pragma unroll
;     for (int i = 0; i < TOT / 512; ++i) {
;         const int idx = tid + 512 * i;
;         int ch, j;
;         if (NCH == 16) { ch = (idx & 7) + 8 * ((idx >> 6) & 1); j = ((idx >> 3) & 7) + 8 * (idx >> 7); } else { ch = idx & 7; j = idx >> 3; }
;         const long r = r0 + j;
;         u32x4 v = {0u, 0u, 0u, 0u};
;         if (r >= rmin) v = STG_NT ? __builtin_nontemporal_load((const u32x4*)(src + r * ld + col0 + 8 * ch)) : *(const u32x4*)(src + r * ld + col0 + 8 * ch);
;         LAS bf16_t* d = dstT + (8 * ch) * VS + (j ^ ((ch & 15) << 3));
;         d[0 * VS] = (bf16_t)(v.x & 0xffffu); d[1 * VS] = (bf16_t)(v.x >> 16); d[2 * VS] = (bf16_t)(v.y & 0xffffu); d[3 * VS] = (bf16_t)(v.y >> 16);
;         d[4 * VS] = (bf16_t)(v.z & 0xffffu); d[5 * VS] = (bf16_t)(v.z >> 16); d[6 * VS] = (bf16_t)(v.w & 0xffffu); d[7 * VS] = (bf16_t)(v.w >> 16);
;     }
; }
; __device__ __forceinline__ void ro_item2(int it0, LAS unsigned char* lds, const bf16_t* RQ, const bf16_t* RK, const bf16_t* RV, const bf16_t* RG, const bf16_t* SPREV, const float* GN, bf16_t* MIX,
;                                          int tid, int wid, int lane) {
;     ...
;     __syncthreads();
; #pragma unroll
;     for (int k = 0; k < 2; ++k) {
;         const int it = it0 + k, bh = it >> 5, n = it & 31, b = bh >> 3, h = bh & 7;
;         stage_T<128, 128, VS>(L + k * TILE, RV, (long)b * SEQ + n * 128, 1024, h * 128, 0, tid);
;     }
.LBB0_1220:
	s_ashr_i32 s34, s50, 8
	s_ashr_i32 s35, s34, 31
	s_lshl_b32 s33, s50, 7
	s_lshl_b64 s[46:47], s[34:35], 12
	s_and_b32 s33, s33, 0xf00
	s_lshl_b32 s35, s50, 3
	s_or_b32 s33, s46, s33
	s_and_b32 s42, s35, 0x700
	s_cmp_gt_i32 s34, -1
	v_lshl_add_u64 v[6:7], v[116:117], 0, s[42:43]
	s_cselect_b64 s[48:49], -1, 0
	s_cmp_lt_i32 s34, 0
	s_waitcnt vmcnt(0)
	s_barrier
	s_cbranch_scc1 .LBB0_1222
	v_mov_b32_e32 v3, s47
	v_or_b32_e32 v2, s33, v118
	v_lshlrev_b64 v[2:3], 11, v[2:3]
	v_lshl_add_u64 v[2:3], v[6:7], 0, v[2:3]
	global_load_dwordx4 v[192:195], v[2:3], off
	s_branch .LBB0_1223
.LBB0_1222:
	v_mov_b32_e32 v192, 0
	v_mov_b32_e32 v193, 0
	v_mov_b32_e32 v194, 0
	v_mov_b32_e32 v195, 0
.LBB0_1223:
	v_cndmask_b32_e64 v2, 0, 1, s[48:49]
	v_cmp_ne_u32_e64 s[34:35], 1, v2
	s_andn2_b64 vcc, exec, s[48:49]
	s_cbranch_vccnz .LBB0_1225
	v_mov_b32_e32 v3, s47
	v_or_b32_e32 v2, s33, v120
	v_lshlrev_b64 v[2:3], 11, v[2:3]
	v_lshl_add_u64 v[2:3], v[6:7], 0, v[2:3]
	global_load_dwordx4 v[196:199], v[2:3], off
	s_branch .LBB0_1226
.LBB0_1225:
	v_mov_b32_e32 v196, 0
	v_mov_b32_e32 v197, 0
	v_mov_b32_e32 v198, 0
	v_mov_b32_e32 v199, 0
.LBB0_1226:
	s_and_b64 vcc, exec, s[34:35]
	s_cbranch_vccnz .LBB0_1228
	v_mov_b32_e32 v3, s47
	v_or_b32_e32 v2, s33, v122
	v_lshlrev_b64 v[2:3], 11, v[2:3]
	v_lshl_add_u64 v[2:3], v[6:7], 0, v[2:3]
	global_load_dwordx4 v[200:203], v[2:3], off
	s_branch .LBB0_1229
.LBB0_1228:
	v_mov_b32_e32 v200, 0
	v_mov_b32_e32 v201, 0
	v_mov_b32_e32 v202, 0
	v_mov_b32_e32 v203, 0
.LBB0_1229:
	s_and_b64 vcc, exec, s[34:35]
	s_cbranch_vccnz .LBB0_1231
	v_mov_b32_e32 v3, s47
	v_or_b32_e32 v2, s33, v124
	v_lshlrev_b64 v[2:3], 11, v[2:3]
	v_lshl_add_u64 v[2:3], v[6:7], 0, v[2:3]
	global_load_dwordx4 v[204:207], v[2:3], off
	s_branch .LBB0_1232
.LBB0_1231:
	v_mov_b32_e32 v204, 0
	v_mov_b32_e32 v205, 0
	v_mov_b32_e32 v206, 0
	v_mov_b32_e32 v207, 0
.LBB0_1232:
	s_and_b64 vcc, exec, s[34:35]
	s_or_b32 s46, s33, 0x80
	s_cbranch_vccnz .LBB0_1234
	v_mov_b32_e32 v3, s47
	v_or_b32_e32 v2, s46, v118
	v_lshlrev_b64 v[2:3], 11, v[2:3]
	v_lshl_add_u64 v[2:3], v[6:7], 0, v[2:3]
	global_load_dwordx4 v[208:211], v[2:3], off
	s_branch .LBB0_1235
.LBB0_1234:
	v_mov_b32_e32 v208, 0
	v_mov_b32_e32 v209, 0
	v_mov_b32_e32 v210, 0
	v_mov_b32_e32 v211, 0
.LBB0_1235:
	s_and_b64 vcc, exec, s[34:35]
	s_cbranch_vccnz .LBB0_1237
	v_mov_b32_e32 v3, s47
	v_or_b32_e32 v2, s46, v120
	v_lshlrev_b64 v[2:3], 11, v[2:3]
	v_lshl_add_u64 v[2:3], v[6:7], 0, v[2:3]
	global_load_dwordx4 v[212:215], v[2:3], off
	s_branch .LBB0_1238
.LBB0_1237:
	v_mov_b32_e32 v212, 0
	v_mov_b32_e32 v213, 0
	v_mov_b32_e32 v214, 0
	v_mov_b32_e32 v215, 0
.LBB0_1238:
	s_and_b64 vcc, exec, s[34:35]
	s_cbranch_vccnz .LBB0_1240
	v_mov_b32_e32 v3, s47
	v_or_b32_e32 v2, s46, v122
	v_lshlrev_b64 v[2:3], 11, v[2:3]
	v_lshl_add_u64 v[2:3], v[6:7], 0, v[2:3]
	global_load_dwordx4 v[216:219], v[2:3], off
	s_branch .LBB0_1241
.LBB0_1240:
	v_mov_b32_e32 v216, 0
	v_mov_b32_e32 v217, 0
	v_mov_b32_e32 v218, 0
	v_mov_b32_e32 v219, 0
.LBB0_1241:
	v_lshl_add_u64 v[8:9], s[46:47], 0, v[124:125]
	v_cmp_lt_i64_e32 vcc, -1, v[8:9]
	v_mov_b32_e32 v220, 0
	v_mov_b32_e32 v221, 0
	v_mov_b32_e32 v222, 0
	v_mov_b32_e32 v223, 0
	s_and_saveexec_b64 s[34:35], vcc
	s_cbranch_execz .LBB0_1243
	v_lshlrev_b64 v[2:3], 11, v[8:9]
	v_lshl_add_u64 v[2:3], v[6:7], 0, v[2:3]
	global_load_dwordx4 v[220:223], v[2:3], off
; #define LAS __attribute__((address_space(3)))
; __device__ __forceinline__ void ro_item2(int it0, LAS unsigned char* lds, const bf16_t* RQ, const bf16_t* RK, const bf16_t* RV, const bf16_t* RG, const bf16_t* SPREV, const float* GN, bf16_t* MIX,
;                                          int tid, int wid, int lane) {
;     ...
; #pragma unroll
;     for (int k = 0; k < 2; ++k) {
;         const int it = it0 + k, bh = it >> 5, n = it & 31, b = bh >> 3, h = bh & 7;
;         stage_T<128, 128, VS>(L + k * TILE, RV, (long)b * SEQ + n * 128, 1024, h * 128, 0, tid);
;     }
;     __syncthreads();
;     const int half = wid >> 2, it = it0 + half, bh = it >> 5, n = it & 31, b = bh >> 3, h = bh & 7;
;     const LAS bf16_t* VT = L + half * TILE;
;     const long r0 = (long)b * SEQ + n * 128;
;     const int x = lane & 31, hi = lane >> 5, ct = wid & 3;
;     const long qrow = r0 + 32 * ct + x;
;     bf16x8 qf[8];
; #pragma unroll
;     for (int ks = 0; ks < 8; ++ks) qf[ks] = *(const bf16x8*)(RQ + qrow * 1024 + h * 128 + 16 * ks + 8 * hi);
;     f32x16 o[4];
; #pragma unroll
;     for (int et = 0; et < 4; ++et) o[et] = f32x16{};
.LBB0_1243:
	s_or_b64 exec, exec, s[34:35]
	s_add_i32 s34, s50, s51
	s_ashr_i32 s46, s34, 8
	s_ashr_i32 s47, s46, 31
	s_lshl_b32 s33, s34, 7
	s_lshl_b64 s[46:47], s[46:47], 12
	s_and_b32 s33, s33, 0xf80
	s_or_b32 s35, s46, s33
	v_mov_b32_e32 v143, s47
	v_or_b32_e32 v142, s35, v128
	s_lshl_b32 s33, s34, 2
	v_lshlrev_b64 v[144:145], 11, v[142:143]
	s_and_b32 s33, s33, 0x380
	s_waitcnt vmcnt(0)
	ds_write_b16 v119, v192
	ds_write_b16_d16_hi v119, v192 offset:272
	ds_write_b16 v119, v193 offset:544
	ds_write_b16_d16_hi v119, v193 offset:816
	ds_write_b16 v119, v194 offset:1088
	ds_write_b16_d16_hi v119, v194 offset:1360
	ds_write_b16 v119, v195 offset:1632
	ds_write_b16_d16_hi v119, v195 offset:1904
	ds_write_b16 v121, v196
	ds_write_b16_d16_hi v121, v196 offset:272
	ds_write_b16 v121, v197 offset:544
	ds_write_b16_d16_hi v121, v197 offset:816
	ds_write_b16 v121, v198 offset:1088
	ds_write_b16_d16_hi v121, v198 offset:1360
	ds_write_b16 v121, v199 offset:1632
	ds_write_b16_d16_hi v121, v199 offset:1904
	ds_write_b16 v133, v200
	ds_write_b16_d16_hi v133, v200 offset:272
	ds_write_b16 v133, v201 offset:544
	ds_write_b16_d16_hi v133, v201 offset:816
	ds_write_b16 v133, v202 offset:1088
	ds_write_b16_d16_hi v133, v202 offset:1360
	ds_write_b16 v133, v203 offset:1632
	ds_write_b16_d16_hi v133, v203 offset:1904
	ds_write_b16 v148, v204
	ds_write_b16_d16_hi v148, v204 offset:272
	ds_write_b16 v148, v205 offset:544
	ds_write_b16_d16_hi v148, v205 offset:816
	ds_write_b16 v148, v206 offset:1088
	ds_write_b16_d16_hi v148, v206 offset:1360
	ds_write_b16 v148, v207 offset:1632
	ds_write_b16_d16_hi v148, v207 offset:1904
	ds_write_b16 v119, v208 offset:34816
	ds_write_b16_d16_hi v119, v208 offset:35088
	ds_write_b16 v119, v209 offset:35360
	ds_write_b16_d16_hi v119, v209 offset:35632
	ds_write_b16 v119, v210 offset:35904
	ds_write_b16_d16_hi v119, v210 offset:36176
	ds_write_b16 v119, v211 offset:36448
	ds_write_b16_d16_hi v119, v211 offset:36720
	ds_write_b16 v121, v212 offset:34816
	ds_write_b16_d16_hi v121, v212 offset:35088
	ds_write_b16 v121, v213 offset:35360
	ds_write_b16_d16_hi v121, v213 offset:35632
	ds_write_b16 v121, v214 offset:35904
	ds_write_b16_d16_hi v121, v214 offset:36176
	ds_write_b16 v121, v215 offset:36448
	ds_write_b16_d16_hi v121, v215 offset:36720
	ds_write_b16 v133, v216 offset:34816
	ds_write_b16_d16_hi v133, v216 offset:35088
	ds_write_b16 v133, v217 offset:35360
	ds_write_b16_d16_hi v133, v217 offset:35632
	ds_write_b16 v133, v218 offset:35904
	ds_write_b16_d16_hi v133, v218 offset:36176
	ds_write_b16 v133, v219 offset:36448
	ds_write_b16_d16_hi v133, v219 offset:36720
	ds_write_b16 v148, v220 offset:34816
	ds_write_b16_d16_hi v148, v220 offset:35088
	ds_write_b16 v148, v221 offset:35360
	ds_write_b16_d16_hi v148, v221 offset:35632
	ds_write_b16 v148, v222 offset:35904
	ds_write_b16_d16_hi v148, v222 offset:36176
	ds_write_b16 v148, v223 offset:36448
	ds_write_b16_d16_hi v148, v223 offset:36720
	v_lshl_add_u64 v[2:3], s[94:95], 0, v[144:145]
	s_lshl_b32 s42, s33, 1
	v_lshl_add_u64 v[2:3], v[2:3], 0, s[42:43]
	v_lshl_add_u64 v[2:3], v[2:3], 0, v[114:115]
	s_waitcnt lgkmcnt(0)
	s_barrier
	global_load_dwordx4 v[110:113], v[2:3], off
	global_load_dwordx4 v[106:109], v[2:3], off offset:32
	global_load_dwordx4 v[102:105], v[2:3], off offset:64
	global_load_dwordx4 v[98:101], v[2:3], off offset:96
	global_load_dwordx4 v[94:97], v[2:3], off offset:128
	global_load_dwordx4 v[90:93], v[2:3], off offset:160
	global_load_dwordx4 v[86:89], v[2:3], off offset:192
	global_load_dwordx4 v[82:85], v[2:3], off offset:224
	s_andn2_b64 vcc, exec, s[44:45]
	s_mov_b32 s48, s47
	s_cbranch_vccnz .LBB0_1218
	s_lshl_b32 s59, s57, 1
	s_and_b32 s49, s55, 0xf80
	s_and_b32 s59, s59, 0x700
	s_add_u32 s46, s49, s46
	s_addc_u32 s47, 0, s47
	v_lshl_add_u64 v[2:3], s[46:47], 0, v[126:127]
	v_lshlrev_b64 v[2:3], 11, v[2:3]
	v_or_b32_e32 v2, s59, v2
	v_lshl_add_u64 v[146:147], v[138:139], 0, v[2:3]
	v_mov_b32_e32 v2, 0
	v_mov_b32_e32 v141, v174
	v_mov_b32_e32 v175, v132
	s_mov_b32 s46, s52
	v_mov_b32_e32 v3, v2
	v_mov_b32_e32 v4, v2
	v_mov_b32_e32 v5, v2
	v_mov_b32_e32 v6, v2
	v_mov_b32_e32 v7, v2
	v_mov_b32_e32 v8, v2
	v_mov_b32_e32 v9, v2
	v_mov_b32_e32 v10, v2
	v_mov_b32_e32 v11, v2
	v_mov_b32_e32 v12, v2
	v_mov_b32_e32 v13, v2
	v_mov_b32_e32 v14, v2
	v_mov_b32_e32 v15, v2
	v_mov_b32_e32 v16, v2
	v_mov_b32_e32 v17, v2
	v_mov_b32_e32 v18, v2
	v_mov_b32_e32 v19, v2
	v_mov_b32_e32 v20, v2
	v_mov_b32_e32 v21, v2
	v_mov_b32_e32 v22, v2
	v_mov_b32_e32 v23, v2
	v_mov_b32_e32 v24, v2
	v_mov_b32_e32 v25, v2
	v_mov_b32_e32 v26, v2
	v_mov_b32_e32 v27, v2
	v_mov_b32_e32 v28, v2
	v_mov_b32_e32 v29, v2
	v_mov_b32_e32 v30, v2
	v_mov_b32_e32 v31, v2
	v_mov_b32_e32 v32, v2
	v_mov_b32_e32 v33, v2
	v_mov_b32_e32 v34, v2
	v_mov_b32_e32 v35, v2
	v_mov_b32_e32 v36, v2
	v_mov_b32_e32 v37, v2
	v_mov_b32_e32 v38, v2
	v_mov_b32_e32 v39, v2
	v_mov_b32_e32 v40, v2
	v_mov_b32_e32 v41, v2
	v_mov_b32_e32 v42, v2
	v_mov_b32_e32 v43, v2
	v_mov_b32_e32 v44, v2
	v_mov_b32_e32 v45, v2
	v_mov_b32_e32 v46, v2
	v_mov_b32_e32 v47, v2
	v_mov_b32_e32 v48, v2
	v_mov_b32_e32 v49, v2
	v_mov_b32_e32 v50, v2
	v_mov_b32_e32 v51, v2
	v_mov_b32_e32 v52, v2
	v_mov_b32_e32 v53, v2
	v_mov_b32_e32 v54, v2
	v_mov_b32_e32 v55, v2
	v_mov_b32_e32 v56, v2
	v_mov_b32_e32 v57, v2
	v_mov_b32_e32 v58, v2
	v_mov_b32_e32 v59, v2
	v_mov_b32_e32 v60, v2
	v_mov_b32_e32 v61, v2
	v_mov_b32_e32 v62, v2
	v_mov_b32_e32 v63, v2
	v_mov_b32_e32 v64, v2
	v_mov_b32_e32 v65, v2
